# attention unit prologue: first K/V tile loads issued with the Q-row loads (their latency no longer exposed before the first LDS write)
# speedup vs baseline: 1.0000x; 1.0000x over previous
; __device__ __forceinline__ int otid() { int t = threadIdx.x; asm volatile("" : "+v"(t)); return t; }
; __device__ __forceinline__ void attn_unit(int bh, int qb, const bf16_t* QKV, const bf16_t* KF, const float* cstab, const float* qg, bf16_t* MIX, LAS unsigned char* lds) {
;     const int tid = otid(), lane = tid & 63, r32 = lane & 31, hi = lane >> 5, wid = __builtin_amdgcn_readfirstlane(tid >> 6);
;     const int b = bh >> 3, h = bh & 7, q0 = qb * 256, qw = q0 + 32 * wid, q = qw + r32;
;     bf16x8 qf[6];
;     {
;         const bf16_t* Qp = QKV + (size_t)(b * SEQ + q) * 1792 + h * 96 + 8 * hi;
;         const float* cs = cstab + (size_t)(b * SEQ + q) * 32 + 8 * hi;
;         u32x4 raw[6];
; #pragma unroll
;         for (int d0 = 0; d0 < 6; ++d0) raw[d0] = *(const u32x4*)(Qp + 16 * d0);
;     ...
;     const char* Kg = (const char*)(KF + (size_t)bh * SEQ * 96);
;     const char* Vg = (const char*)(QKV + (size_t)b * SEQ * 1792 + 768 + h * 128 + 64) + (size_t)(tid >> 3) * 3584 + (tid & 7) * 16;
;     const int kofs0 = (tid / 12) * KROW + (tid % 12) * 16, kofs1 = ((tid + 512) / 12) * KROW + ((tid + 512) % 12) * 16, vofs = KBUF + (tid >> 3) * VROW + (tid & 7) * 16;
;     const int vtb = KBUF + (4 * hi + ((lane & 15) >> 2)) * VROW + (16 * ((lane >> 4) & 1) + 4 * (lane & 3)) * 2;
;     const int NT = 4 * (qb + 1);
;     u32x4 kr0, kr1 = {0u, 0u, 0u, 0u}, vr;
.LBB0_1037:
	v_mov_b32_e32 v143, v228
	s_and_b32 s29, s27, 7
	s_xor_b32 s23, s29, 15
	v_readfirstlane_b32 s2, v143
	s_ashr_i32 s39, s2, 6
	s_lshl_b32 s22, s23, 8
	s_lshl_b32 s37, s39, 5
	s_ashr_i32 s4, s27, 3
	v_and_b32_e32 v138, 31, v143
	s_ashr_i32 s2, s27, 6
	s_add_i32 s37, s37, s22
	s_and_b32 s36, s4, 7
	v_or_b32_e32 v139, s37, v138
	s_lshl_b32 s28, s2, 12
	s_waitcnt vmcnt(5)
	v_add_u32_e32 v24, s28, v139
	v_mov_b64_e32 v[0:1], s[80:81]
	s_mul_i32 s5, s36, 0x60
	v_bfe_u32 v144, v143, 5, 1
	v_mad_i64_i32 v[0:1], s[6:7], v24, s85, v[0:1]
	s_lshl_b32 s78, s5, 1
	v_lshl_add_u64 v[0:1], v[0:1], 0, s[78:79]
	v_lshlrev_b32_e32 v102, 4, v144
	v_mov_b32_e32 v103, v65
	v_lshl_add_u64 v[0:1], v[0:1], 0, v[102:103]
	global_load_dwordx4 v[56:59], v[0:1], off offset:128
	global_load_dwordx4 v[60:63], v[0:1], off offset:160
	global_load_dwordx4 v[66:69], v[0:1], off offset:96
	global_load_dwordx4 v[70:73], v[0:1], off offset:64
	global_load_dwordx4 v[74:77], v[0:1], off offset:32
	global_load_dwordx4 v[108:111], v[0:1], off
	v_and_b32_e32 v64, 32, v143
	global_load_dwordx4 v[0:3], v64, s[0:1] offset:272
	global_load_dwordx4 v[12:15], v64, s[0:1] offset:256
	global_load_dwordx4 v[4:7], v64, s[0:1] offset:336
	global_load_dwordx4 v[8:11], v64, s[0:1] offset:320
	global_load_dwordx4 v[16:19], v64, s[0:1] offset:208
	global_load_dwordx4 v[20:23], v64, s[0:1] offset:192
	global_load_dwordx4 v[40:43], v64, s[0:1] offset:144
	global_load_dwordx4 v[44:47], v64, s[0:1] offset:128
	global_load_dwordx4 v[48:51], v64, s[0:1] offset:80
	global_load_dwordx4 v[52:55], v64, s[0:1] offset:64
	v_ashrrev_i32_e32 v25, 31, v24
	v_lshlrev_b64 v[24:25], 7, v[24:25]
	v_lshl_add_u64 v[24:25], s[8:9], 0, v[24:25]
	s_mul_i32 s31, s4, 0xc0000
	v_lshl_add_u64 v[36:37], v[24:25], 0, v[64:65]
	s_mul_hi_i32 s30, s4, 0xc0000
	s_add_u32 s14, s10, s31
	global_load_dwordx4 v[24:27], v[36:37], off offset:16
	global_load_dwordx4 v[32:35], v[36:37], off
	global_load_dwordx4 v[28:31], v[36:37], off offset:80
	s_nop 0
	global_load_dwordx4 v[36:39], v[36:37], off offset:64
	s_addc_u32 s15, s11, s30
	s_movk_i32 s4, 0x100
	v_cmp_gt_i32_e64 s[6:7], s4, v143
	s_mul_i32 s98, s2, 0xe00000
	s_mul_hi_i32 s99, s2, 0xe00000
	s_add_u32 s98, s80, s98
	s_addc_u32 s99, s81, s99
	s_lshl_b32 s100, s36, 8
	s_add_u32 s98, s98, s100
	s_addc_u32 s99, s99, 0
	v_mov_b64_e32 v[166:167], s[98:99]
	v_ashrrev_i32_e32 v164, 3, v143
	v_lshlrev_b32_e32 v168, 4, v143
	v_mad_i64_i32 v[166:167], s[100:101], v164, s85, v[166:167]
	v_and_b32_e32 v164, 0x70, v168
	v_mov_b32_e32 v165, 0
	v_lshl_add_u64 v[166:167], v[166:167], 0, v[164:165]
	global_load_dwordx4 v[156:159], v[166:167], off offset:1664
	v_add_u32_e32 v168, 0x2000, v168
	v_mov_b32_e32 v169, 0
	v_lshl_add_u64 v[168:169], s[14:15], 0, v[168:169]
	global_load_dwordx4 v[160:163], v[168:169], off
	s_waitcnt vmcnt(21)
	v_lshlrev_b32_e32 v96, 16, v59
	v_and_b32_e32 v97, 0xffff0000, v59
	s_waitcnt vmcnt(19)
	v_lshlrev_b32_e32 v90, 16, v69
	v_and_b32_e32 v91, 0xffff0000, v69
	v_lshlrev_b32_e32 v92, 16, v68
	s_waitcnt vmcnt(16)
; __device__ __forceinline__ float sum32(float v) { const auto rr = __builtin_amdgcn_permlane32_swap(__float_as_uint(v), __float_as_uint(v), false, false); return __uint_as_float(rr[0]) + __uint_as_float(rr[1]); }
; __device__ __forceinline__ void attn_unit(int bh, int qb, const bf16_t* QKV, const bf16_t* KF, const float* cstab, const float* qg, bf16_t* MIX, LAS unsigned char* lds) {
;     ...
;         float ss = 0.f;
; #pragma unroll
;         for (int d0 = 0; d0 < 6; ++d0) { float v[8]; unpack8(raw[d0], v);
; #pragma unroll
;             for (int i = 0; i < 8; ++i) ss += v[i] * v[i]; }
;         ss = pg8::sum32(ss);
;         const float rs = __builtin_amdgcn_rsqf(ss * (1.0f / 96.0f) + EPS) * C2Q;
	v_lshlrev_b32_e32 v132, 16, v108
	v_and_b32_e32 v133, 0xffff0000, v108
	v_lshlrev_b32_e32 v108, 4, v143
	v_lshlrev_b32_e32 v130, 16, v109
	v_and_b32_e32 v131, 0xffff0000, v109
	v_ashrrev_i32_e32 v109, 31, v108
	v_and_b32_e32 v93, 0xffff0000, v68
	v_lshl_add_u64 v[68:69], s[14:15], 0, v[108:109]
	v_lshlrev_b32_e32 v94, 16, v63
	v_and_b32_e32 v95, 0xffff0000, v63
	v_lshlrev_b32_e32 v100, 16, v58
	v_and_b32_e32 v101, 0xffff0000, v58
	v_lshlrev_b32_e32 v98, 16, v62
	v_and_b32_e32 v99, 0xffff0000, v62
	v_lshlrev_b32_e32 v112, 16, v57
	v_and_b32_e32 v113, 0xffff0000, v57
	v_lshlrev_b32_e32 v106, 16, v61
	v_and_b32_e32 v107, 0xffff0000, v61
	v_lshlrev_b32_e32 v116, 16, v56
	v_and_b32_e32 v117, 0xffff0000, v56
	v_lshlrev_b32_e32 v114, 16, v60
	v_and_b32_e32 v115, 0xffff0000, v60
	v_lshlrev_b32_e32 v82, 16, v73
	v_and_b32_e32 v83, 0xffff0000, v73
	v_lshlrev_b32_e32 v84, 16, v72
	v_and_b32_e32 v85, 0xffff0000, v72
	v_lshlrev_b32_e32 v122, 16, v71
	v_and_b32_e32 v123, 0xffff0000, v71
	v_lshlrev_b32_e32 v124, 16, v70
	v_and_b32_e32 v125, 0xffff0000, v70
	global_load_dwordx4 v[56:59], v64, s[0:1] offset:16
	global_load_dwordx4 v[60:63], v64, s[0:1]
	global_load_dwordx4 v[70:73], v[68:69], off
	v_mul_f32_e32 v64, v133, v133
	v_lshlrev_b32_e32 v118, 16, v67
	v_and_b32_e32 v119, 0xffff0000, v67
	v_lshlrev_b32_e32 v120, 16, v66
	v_and_b32_e32 v121, 0xffff0000, v66
	v_pk_fma_f32 v[66:67], v[132:133], v[132:133], v[64:65] op_sel_hi:[1,1,0]
	v_mul_f32_e32 v64, v131, v131
	v_pk_fma_f32 v[66:67], v[130:131], v[130:131], v[66:67]
	v_lshlrev_b32_e32 v128, 16, v110
	v_and_b32_e32 v129, 0xffff0000, v110
	v_pk_add_f32 v[66:67], v[64:65], v[66:67] op_sel_hi:[0,1]
	v_pk_fma_f32 v[66:67], v[128:129], v[128:129], v[66:67]
	v_mul_f32_e32 v64, v129, v129
	v_lshlrev_b32_e32 v126, 16, v111
	v_and_b32_e32 v127, 0xffff0000, v111
	v_pk_add_f32 v[66:67], v[64:65], v[66:67] op_sel_hi:[0,1]
	v_pk_fma_f32 v[66:67], v[126:127], v[126:127], v[66:67]
	v_mul_f32_e32 v64, v127, v127
	v_lshlrev_b32_e32 v88, 16, v74
	v_and_b32_e32 v89, 0xffff0000, v74
	v_pk_add_f32 v[66:67], v[64:65], v[66:67] op_sel_hi:[0,1]
	v_pk_fma_f32 v[66:67], v[88:89], v[88:89], v[66:67]
	v_mul_f32_e32 v64, v89, v89
	v_lshlrev_b32_e32 v86, 16, v75
	v_and_b32_e32 v87, 0xffff0000, v75
	v_pk_add_f32 v[66:67], v[64:65], v[66:67] op_sel_hi:[0,1]
	v_pk_fma_f32 v[66:67], v[86:87], v[86:87], v[66:67]
	v_mul_f32_e32 v64, v87, v87
	v_lshlrev_b32_e32 v80, 16, v76
	v_and_b32_e32 v81, 0xffff0000, v76
	v_pk_add_f32 v[66:67], v[64:65], v[66:67] op_sel_hi:[0,1]
	v_pk_fma_f32 v[66:67], v[80:81], v[80:81], v[66:67]
	v_mul_f32_e32 v64, v81, v81
	v_lshlrev_b32_e32 v78, 16, v77
	v_and_b32_e32 v79, 0xffff0000, v77
	v_pk_add_f32 v[66:67], v[64:65], v[66:67] op_sel_hi:[0,1]
	v_pk_fma_f32 v[66:67], v[78:79], v[78:79], v[66:67]
	v_mul_f32_e32 v64, v79, v79
	v_pk_add_f32 v[66:67], v[64:65], v[66:67] op_sel_hi:[0,1]
	v_pk_fma_f32 v[66:67], v[124:125], v[124:125], v[66:67]
	v_mul_f32_e32 v64, v125, v125
	v_pk_add_f32 v[66:67], v[64:65], v[66:67] op_sel_hi:[0,1]
	v_pk_fma_f32 v[66:67], v[122:123], v[122:123], v[66:67]
	v_mul_f32_e32 v64, v123, v123
	v_pk_add_f32 v[66:67], v[64:65], v[66:67] op_sel_hi:[0,1]
	v_pk_fma_f32 v[66:67], v[84:85], v[84:85], v[66:67]
	v_mul_f32_e32 v64, v85, v85
	v_pk_add_f32 v[66:67], v[64:65], v[66:67] op_sel_hi:[0,1]
	v_pk_fma_f32 v[66:67], v[82:83], v[82:83], v[66:67]
	v_mul_f32_e32 v64, v83, v83
	v_pk_add_f32 v[66:67], v[64:65], v[66:67] op_sel_hi:[0,1]
	v_pk_fma_f32 v[66:67], v[120:121], v[120:121], v[66:67]
	v_mul_f32_e32 v64, v121, v121
	v_pk_add_f32 v[66:67], v[64:65], v[66:67] op_sel_hi:[0,1]
	v_pk_fma_f32 v[66:67], v[118:119], v[118:119], v[66:67]
	v_mul_f32_e32 v64, v119, v119
	v_pk_add_f32 v[66:67], v[64:65], v[66:67] op_sel_hi:[0,1]
	v_pk_fma_f32 v[66:67], v[92:93], v[92:93], v[66:67]
	v_mul_f32_e32 v64, v93, v93
	v_pk_add_f32 v[66:67], v[64:65], v[66:67] op_sel_hi:[0,1]
	v_pk_fma_f32 v[66:67], v[90:91], v[90:91], v[66:67]
	v_mul_f32_e32 v64, v91, v91
	v_pk_add_f32 v[66:67], v[64:65], v[66:67] op_sel_hi:[0,1]
	v_pk_fma_f32 v[66:67], v[116:117], v[116:117], v[66:67]
	v_mul_f32_e32 v64, v117, v117
	v_pk_add_f32 v[66:67], v[64:65], v[66:67] op_sel_hi:[0,1]
	v_pk_fma_f32 v[66:67], v[112:113], v[112:113], v[66:67]
	v_mul_f32_e32 v64, v113, v113
	v_pk_add_f32 v[66:67], v[64:65], v[66:67] op_sel_hi:[0,1]
	v_pk_fma_f32 v[66:67], v[100:101], v[100:101], v[66:67]
	v_mul_f32_e32 v64, v101, v101
	v_pk_add_f32 v[66:67], v[64:65], v[66:67] op_sel_hi:[0,1]
	v_pk_fma_f32 v[66:67], v[96:97], v[96:97], v[66:67]
	v_mul_f32_e32 v64, v97, v97
	v_pk_add_f32 v[66:67], v[64:65], v[66:67] op_sel_hi:[0,1]
	v_pk_fma_f32 v[66:67], v[114:115], v[114:115], v[66:67]
	v_mul_f32_e32 v64, v115, v115
	v_pk_add_f32 v[66:67], v[64:65], v[66:67] op_sel_hi:[0,1]
	v_pk_fma_f32 v[66:67], v[106:107], v[106:107], v[66:67]
	v_mul_f32_e32 v64, v107, v107
	v_pk_add_f32 v[66:67], v[64:65], v[66:67] op_sel_hi:[0,1]
	v_pk_fma_f32 v[66:67], v[98:99], v[98:99], v[66:67]
	v_mul_f32_e32 v64, v99, v99
	v_pk_add_f32 v[66:67], v[64:65], v[66:67] op_sel_hi:[0,1]
	v_pk_fma_f32 v[66:67], v[94:95], v[94:95], v[66:67]
	v_mul_f32_e32 v64, v95, v95
	v_pk_add_f32 v[134:135], v[64:65], v[66:67] op_sel_hi:[0,1]
	v_add_u32_e32 v74, 0x200, v143
	v_mov_b32_e32 v66, v65
	v_mov_b32_e32 v67, v65
	v_mov_b32_e32 v146, v134
	v_mov_b32_e32 v64, v65
	v_lshlrev_b32_e32 v110, 4, v74
	v_mov_b64_e32 v[68:69], v[66:67]
	v_permlane32_swap_b32_e32 v134, v146
	v_ashrrev_i32_e32 v111, 31, v110
	v_mov_b64_e32 v[66:67], v[64:65]
	s_and_saveexec_b64 s[4:5], s[6:7]
	s_cbranch_execz .LBB0_1039
	v_lshl_add_u64 v[66:67], s[14:15], 0, v[110:111]

; __device__ __forceinline__ unsigned cvt_pk_bf16(float lo, float hi) { const f32x2c_ v = {lo, hi}; const bf16x2c_ b = __builtin_convertvector(v, bf16x2c_); return __builtin_bit_cast(unsigned, b); }
; __device__ __forceinline__ float sum32(float v) { const auto rr = __builtin_amdgcn_permlane32_swap(__float_as_uint(v), __float_as_uint(v), false, false); return __uint_as_float(rr[0]) + __uint_as_float(rr[1]); }
; #define LAS __attribute__((address_space(3)))
; __device__ __forceinline__ void attn_unit(int bh, int qb, const bf16_t* QKV, const bf16_t* KF, const float* cstab, const float* qg, bf16_t* MIX, LAS unsigned char* lds) {
;     ...
;     const int b = bh >> 3, h = bh & 7, q0 = qb * 256, qw = q0 + 32 * wid, q = qw + r32;
;     bf16x8 qf[6];
;     {
;         const bf16_t* Qp = QKV + (size_t)(b * SEQ + q) * 1792 + h * 96 + 8 * hi;
;         const float* cs = cstab + (size_t)(b * SEQ + q) * 32 + 8 * hi;
;         u32x4 raw[6];
; #pragma unroll
;         for (int d0 = 0; d0 < 6; ++d0) raw[d0] = *(const u32x4*)(Qp + 16 * d0);
;     ...
;         __syncthreads();
;     }
;     const float l = pg8::sum32(lrun), inv = 1.0f / l;
;     {
;         constexpr int OROW = 144;
;         LAS unsigned char* stg = lds + 2 * BUFB + wid * (32 * OROW);
; #pragma unroll
;         for (int rg = 0; rg < 4; ++rg) {
;             u32x2 w; w.x = cvt_pk_bf16(o0[4 * rg] * inv, o0[4 * rg + 1] * inv); w.y = cvt_pk_bf16(o0[4 * rg + 2] * inv, o0[4 * rg + 3] * inv);
;             u32x2 x; x.x = cvt_pk_bf16(o1[4 * rg] * inv, o1[4 * rg + 1] * inv); x.y = cvt_pk_bf16(o1[4 * rg + 2] * inv, o1[4 * rg + 3] * inv);
;             *(LAS u32x2*)(stg + r32 * OROW + (8 * rg + 4 * hi) * 2) = w; *(LAS u32x2*)(stg + r32 * OROW + (32 + 8 * rg + 4 * hi) * 2) = x;
;         }
;         asm volatile("s_waitcnt lgkmcnt(0)" ::: "memory");
;         bf16_t* dst = MIX + ((size_t)(b * SEQ + qw)) * 1024 + h * 64 + (lane & 7) * 8;
; #pragma unroll
;         for (int it = 0; it < 4; ++it) { const int row = it * 8 + (lane >> 3); const u32x4 v = *(const LAS u32x4*)(stg + row * OROW + (lane & 7) * 16); *(u32x4*)(dst + (size_t)row * 1024) = v; }
.LBB0_1077:
	s_add_i32 s40, s40, 1
	v_lshl_add_u64 v[112:113], v[112:113], 0, s[82:83]
	v_lshl_add_u64 v[108:109], v[108:109], 0, s[96:97]
	s_cmp_lg_u32 s42, s22
	v_lshl_add_u64 v[110:111], v[110:111], 0, s[96:97]
	s_waitcnt lgkmcnt(0)
	s_barrier
	s_cbranch_scc1 .LBB0_1057
	v_mov_b32_e32 v32, v107
	s_nop 1
	v_permlane32_swap_b32_e32 v107, v32
	v_add_f32_e32 v32, v107, v32
	v_div_scale_f32 v33, s[4:5], v32, v32, 1.0
	v_rcp_f32_e32 v34, v33
	s_mulk_i32 s39, 0x1200
	s_add_i32 s2, s39, 0
	s_add_i32 s4, s37, s28
	v_fma_f32 v35, -v33, v34, 1.0
	v_fmac_f32_e32 v34, v35, v34
	v_div_scale_f32 v35, vcc, 1.0, v32, 1.0
	v_mul_f32_e32 v36, v35, v34
	v_fma_f32 v37, -v33, v36, v35
	v_fmac_f32_e32 v36, v37, v34
	v_fma_f32 v33, -v33, v36, v35
	v_div_fmas_f32 v33, v33, v34, v36
	v_div_fixup_f32 v32, v33, v32, 1.0
	v_mul_u32_u24_e32 v33, 0x90, v138
	v_add3_u32 v33, s2, v33, v117
	v_pk_mul_f32 v[0:1], v[0:1], v[32:33] op_sel_hi:[1,0]
	v_pk_mul_f32 v[2:3], v[2:3], v[32:33] op_sel_hi:[1,0]
	v_cvt_pk_bf16_f32 v0, v0, v1
	v_cvt_pk_bf16_f32 v1, v2, v3
	v_pk_mul_f32 v[2:3], v[16:17], v[32:33] op_sel_hi:[1,0]
	v_pk_mul_f32 v[16:17], v[18:19], v[32:33] op_sel_hi:[1,0]
	v_pk_mul_f32 v[4:5], v[4:5], v[32:33] op_sel_hi:[1,0]
	v_pk_mul_f32 v[6:7], v[6:7], v[32:33] op_sel_hi:[1,0]
	v_cvt_pk_bf16_f32 v2, v2, v3
	v_cvt_pk_bf16_f32 v3, v16, v17
	v_cvt_pk_bf16_f32 v4, v4, v5
	v_cvt_pk_bf16_f32 v5, v6, v7
	v_pk_mul_f32 v[6:7], v[20:21], v[32:33] op_sel_hi:[1,0]
	v_pk_mul_f32 v[16:17], v[22:23], v[32:33] op_sel_hi:[1,0]
	v_cvt_pk_bf16_f32 v6, v6, v7
	v_cvt_pk_bf16_f32 v7, v16, v17
	v_add_u32_e32 v16, 0xc800, v33
	ds_write2_b64 v16, v[0:1], v[4:5] offset1:2
	ds_write2_b64 v16, v[2:3], v[6:7] offset0:8 offset1:10
	v_pk_mul_f32 v[0:1], v[8:9], v[32:33] op_sel_hi:[1,0]
	v_pk_mul_f32 v[2:3], v[10:11], v[32:33] op_sel_hi:[1,0]
	v_cvt_pk_bf16_f32 v0, v0, v1
	v_cvt_pk_bf16_f32 v1, v2, v3
	v_pk_mul_f32 v[2:3], v[24:25], v[32:33] op_sel_hi:[1,0]
	v_pk_mul_f32 v[4:5], v[26:27], v[32:33] op_sel_hi:[1,0]
	v_cvt_pk_bf16_f32 v2, v2, v3
	v_cvt_pk_bf16_f32 v3, v4, v5
	v_pk_mul_f32 v[4:5], v[12:13], v[32:33] op_sel_hi:[1,0]
	v_pk_mul_f32 v[6:7], v[14:15], v[32:33] op_sel_hi:[1,0]
	v_cvt_pk_bf16_f32 v4, v4, v5
	v_cvt_pk_bf16_f32 v5, v6, v7
	v_pk_mul_f32 v[6:7], v[28:29], v[32:33] op_sel_hi:[1,0]
	v_pk_mul_f32 v[8:9], v[30:31], v[32:33] op_sel_hi:[1,0]
	s_ashr_i32 s5, s4, 31
	v_cvt_pk_bf16_f32 v6, v6, v7
	v_cvt_pk_bf16_f32 v7, v8, v9
	ds_write2_b64 v16, v[0:1], v[4:5] offset0:4 offset1:6
	ds_write2_b64 v16, v[2:3], v[6:7] offset0:12 offset1:14
	s_lshl_b64 s[4:5], s[4:5], 11
	v_lshrrev_b32_e32 v4, 3, v116
	s_add_u32 s4, s16, s4
	v_mul_u32_u24_e32 v0, 0x90, v4
	s_waitcnt lgkmcnt(0)
	s_addc_u32 s5, s17, s5
	s_lshl_b32 s6, s36, 7
	v_add3_u32 v12, s2, v64, v0
	s_add_u32 s4, s4, s6
	ds_read_b128 v[0:3], v12 offset:51200
	s_addc_u32 s5, s5, 0
	v_lshl_add_u64 v[8:9], s[4:5], 0, v[64:65]
	v_lshlrev_b32_e32 v64, 11, v4
	ds_read_b128 v[4:7], v12 offset:52352
	v_lshl_add_u64 v[10:11], v[8:9], 0, v[64:65]
	s_waitcnt lgkmcnt(1)
	global_store_dwordx4 v[10:11], v[0:3], off
	v_or_b32_e32 v10, 0x8000, v64
	v_mov_b32_e32 v11, v65
	v_or_b32_e32 v0, 0x4000, v64
	v_mov_b32_e32 v1, v65
	v_lshl_add_u64 v[0:1], v[8:9], 0, v[0:1]
	s_waitcnt lgkmcnt(0)
	global_store_dwordx4 v[0:1], v[4:7], off
	ds_read_b128 v[0:3], v12 offset:53504
	ds_read_b128 v[4:7], v12 offset:54656
	v_lshl_add_u64 v[10:11], v[8:9], 0, v[10:11]
	v_or_b32_e32 v64, 0xc000, v64
	v_mov_b32_e32 v143, v228
	s_waitcnt lgkmcnt(1)
	global_store_dwordx4 v[10:11], v[0:3], off
	v_mov_b32_e32 v103, v65
	s_nop 0
	v_lshl_add_u64 v[0:1], v[8:9], 0, v[64:65]
	s_waitcnt lgkmcnt(0)
	global_store_dwordx4 v[0:1], v[4:7], off
	v_mov_b64_e32 v[2:3], s[80:81]
	v_readfirstlane_b32 s2, v143
	s_ashr_i32 s23, s2, 6
	s_lshl_b32 s2, s29, 8
	s_lshl_b32 s22, s23, 5
	v_and_b32_e32 v138, 31, v143
	s_add_i32 s22, s22, s2
	v_or_b32_e32 v139, s22, v138
	v_add_u32_e32 v0, s28, v139
	v_bfe_u32 v144, v143, 5, 1
	v_mad_i64_i32 v[2:3], s[4:5], v0, s85, v[2:3]
	v_lshl_add_u64 v[2:3], v[2:3], 0, s[78:79]
	v_lshlrev_b32_e32 v102, 4, v144
	v_lshl_add_u64 v[2:3], v[2:3], 0, v[102:103]
	global_load_dwordx4 v[32:35], v[2:3], off offset:128
	global_load_dwordx4 v[36:39], v[2:3], off offset:160
	global_load_dwordx4 v[40:43], v[2:3], off offset:96
	global_load_dwordx4 v[48:51], v[2:3], off offset:64
	global_load_dwordx4 v[56:59], v[2:3], off offset:32
	global_load_dwordx4 v[66:69], v[2:3], off
	v_ashrrev_i32_e32 v1, 31, v0
	v_lshlrev_b64 v[0:1], 7, v[0:1]
	v_lshl_add_u64 v[0:1], s[8:9], 0, v[0:1]
	v_and_b32_e32 v64, 32, v143
	v_lshl_add_u64 v[28:29], v[0:1], 0, v[64:65]
	global_load_dwordx4 v[4:7], v64, s[0:1] offset:272
	global_load_dwordx4 v[24:27], v64, s[0:1] offset:256
	global_load_dwordx4 v[8:11], v64, s[0:1] offset:336
	global_load_dwordx4 v[20:23], v64, s[0:1] offset:320
	global_load_dwordx4 v[0:3], v[28:29], off offset:16
	global_load_dwordx4 v[16:19], v[28:29], off
	global_load_dwordx4 v[12:15], v[28:29], off offset:80
	s_nop 0
	global_load_dwordx4 v[28:31], v[28:29], off offset:64
	v_lshlrev_b32_e32 v108, 4, v143
	v_ashrrev_i32_e32 v109, 31, v108
	v_add_u32_e32 v74, 0x200, v143
	s_movk_i32 s2, 0x100
	v_lshlrev_b32_e32 v110, 4, v74
	v_cmp_gt_i32_e64 s[6:7], s2, v143
	v_ashrrev_i32_e32 v111, 31, v110
	v_mov_b64_e32 v[166:167], s[18:19]
	v_ashrrev_i32_e32 v164, 3, v143
	v_lshlrev_b32_e32 v168, 4, v143
	v_mad_i64_i32 v[166:167], s[100:101], v164, s85, v[166:167]
	v_and_b32_e32 v164, 0x70, v168
	v_mov_b32_e32 v165, 0
	v_lshl_add_u64 v[166:167], v[166:167], 0, v[164:165]
	global_load_dwordx4 v[156:159], v[166:167], off offset:1664
	v_add_u32_e32 v168, 0x2000, v168
	v_mov_b32_e32 v169, 0
	v_lshl_add_u64 v[168:169], s[14:15], 0, v[168:169]
	global_load_dwordx4 v[160:163], v[168:169], off
	s_waitcnt vmcnt(15)
; __device__ __forceinline__ float sum32(float v) { const auto rr = __builtin_amdgcn_permlane32_swap(__float_as_uint(v), __float_as_uint(v), false, false); return __uint_as_float(rr[0]) + __uint_as_float(rr[1]); }
; __device__ __forceinline__ void attn_unit(int bh, int qb, const bf16_t* QKV, const bf16_t* KF, const float* cstab, const float* qg, bf16_t* MIX, LAS unsigned char* lds) {
;     ...
;         float ss = 0.f;
; #pragma unroll
;         for (int d0 = 0; d0 < 6; ++d0) { float v[8]; unpack8(raw[d0], v);
; #pragma unroll
;             for (int i = 0; i < 8; ++i) ss += v[i] * v[i]; }
;         ss = pg8::sum32(ss);
;         const float rs = __builtin_amdgcn_rsqf(ss * (1.0f / 96.0f) + EPS) * C2Q;
	v_lshlrev_b32_e32 v94, 16, v35
	v_and_b32_e32 v95, 0xffff0000, v35
	s_waitcnt vmcnt(14)
	v_lshlrev_b32_e32 v96, 16, v39
	v_and_b32_e32 v97, 0xffff0000, v39
	v_lshlrev_b32_e32 v98, 16, v34
	s_waitcnt vmcnt(10)
	v_lshlrev_b32_e32 v126, 16, v69
	v_and_b32_e32 v127, 0xffff0000, v69
	v_lshlrev_b32_e32 v128, 16, v68
	v_and_b32_e32 v129, 0xffff0000, v68
	v_lshl_add_u64 v[68:69], s[14:15], 0, v[108:109]
	v_and_b32_e32 v99, 0xffff0000, v34
	v_lshlrev_b32_e32 v100, 16, v38
	v_and_b32_e32 v101, 0xffff0000, v38
	v_lshlrev_b32_e32 v106, 16, v33
	v_and_b32_e32 v107, 0xffff0000, v33
	v_lshlrev_b32_e32 v112, 16, v37
	v_and_b32_e32 v113, 0xffff0000, v37
	v_lshlrev_b32_e32 v114, 16, v32
	v_and_b32_e32 v115, 0xffff0000, v32
	v_lshlrev_b32_e32 v116, 16, v36
	v_and_b32_e32 v117, 0xffff0000, v36
	v_lshlrev_b32_e32 v90, 16, v43
	v_and_b32_e32 v91, 0xffff0000, v43
	global_load_dwordx4 v[32:35], v64, s[0:1] offset:208
	global_load_dwordx4 v[36:39], v64, s[0:1] offset:192
	v_lshlrev_b32_e32 v92, 16, v42
	v_and_b32_e32 v93, 0xffff0000, v42
	v_lshlrev_b32_e32 v118, 16, v41
	v_and_b32_e32 v119, 0xffff0000, v41
	v_lshlrev_b32_e32 v120, 16, v40
	v_and_b32_e32 v121, 0xffff0000, v40
	v_lshlrev_b32_e32 v82, 16, v51
	v_and_b32_e32 v83, 0xffff0000, v51
	global_load_dwordx4 v[40:43], v64, s[0:1] offset:144
	global_load_dwordx4 v[44:47], v64, s[0:1] offset:128
	v_lshlrev_b32_e32 v84, 16, v50
	v_and_b32_e32 v85, 0xffff0000, v50
	v_lshlrev_b32_e32 v122, 16, v49
	v_and_b32_e32 v123, 0xffff0000, v49
	v_lshlrev_b32_e32 v124, 16, v48
	v_and_b32_e32 v125, 0xffff0000, v48
	v_lshlrev_b32_e32 v78, 16, v59
	v_and_b32_e32 v79, 0xffff0000, v59
	global_load_dwordx4 v[48:51], v64, s[0:1] offset:80
	global_load_dwordx4 v[52:55], v64, s[0:1] offset:64
	v_lshlrev_b32_e32 v80, 16, v58
	v_and_b32_e32 v81, 0xffff0000, v58
	v_lshlrev_b32_e32 v86, 16, v57
	v_and_b32_e32 v87, 0xffff0000, v57
	v_lshlrev_b32_e32 v88, 16, v56
	v_and_b32_e32 v89, 0xffff0000, v56
	global_load_dwordx4 v[56:59], v64, s[0:1] offset:16
	global_load_dwordx4 v[60:63], v64, s[0:1]
	global_load_dwordx4 v[70:73], v[68:69], off
	v_and_b32_e32 v133, 0xffff0000, v66
	v_lshlrev_b32_e32 v132, 16, v66
	v_mul_f32_e32 v64, v133, v133
	v_lshlrev_b32_e32 v130, 16, v67
	v_and_b32_e32 v131, 0xffff0000, v67
	v_pk_fma_f32 v[66:67], v[132:133], v[132:133], v[64:65] op_sel_hi:[1,1,0]
	v_mul_f32_e32 v64, v131, v131
	v_pk_fma_f32 v[66:67], v[130:131], v[130:131], v[66:67]
	s_nop 0
	v_pk_add_f32 v[66:67], v[64:65], v[66:67] op_sel_hi:[0,1]
	v_pk_fma_f32 v[66:67], v[128:129], v[128:129], v[66:67]
	v_mul_f32_e32 v64, v129, v129
	v_pk_add_f32 v[66:67], v[64:65], v[66:67] op_sel_hi:[0,1]
	v_pk_fma_f32 v[66:67], v[126:127], v[126:127], v[66:67]
	v_mul_f32_e32 v64, v127, v127
	v_pk_add_f32 v[66:67], v[64:65], v[66:67] op_sel_hi:[0,1]
	v_pk_fma_f32 v[66:67], v[88:89], v[88:89], v[66:67]
	v_mul_f32_e32 v64, v89, v89
	v_pk_add_f32 v[66:67], v[64:65], v[66:67] op_sel_hi:[0,1]
	v_pk_fma_f32 v[66:67], v[86:87], v[86:87], v[66:67]
	v_mul_f32_e32 v64, v87, v87
	v_pk_add_f32 v[66:67], v[64:65], v[66:67] op_sel_hi:[0,1]
	v_pk_fma_f32 v[66:67], v[80:81], v[80:81], v[66:67]
	v_mul_f32_e32 v64, v81, v81
	v_pk_add_f32 v[66:67], v[64:65], v[66:67] op_sel_hi:[0,1]
	v_pk_fma_f32 v[66:67], v[78:79], v[78:79], v[66:67]
	v_mul_f32_e32 v64, v79, v79
	v_pk_add_f32 v[66:67], v[64:65], v[66:67] op_sel_hi:[0,1]
	v_pk_fma_f32 v[66:67], v[124:125], v[124:125], v[66:67]
	v_mul_f32_e32 v64, v125, v125
	v_pk_add_f32 v[66:67], v[64:65], v[66:67] op_sel_hi:[0,1]
	v_pk_fma_f32 v[66:67], v[122:123], v[122:123], v[66:67]
	v_mul_f32_e32 v64, v123, v123
	v_pk_add_f32 v[66:67], v[64:65], v[66:67] op_sel_hi:[0,1]
	v_pk_fma_f32 v[66:67], v[84:85], v[84:85], v[66:67]
	v_mul_f32_e32 v64, v85, v85
	v_pk_add_f32 v[66:67], v[64:65], v[66:67] op_sel_hi:[0,1]
	v_pk_fma_f32 v[66:67], v[82:83], v[82:83], v[66:67]
	v_mul_f32_e32 v64, v83, v83
	v_pk_add_f32 v[66:67], v[64:65], v[66:67] op_sel_hi:[0,1]
	v_pk_fma_f32 v[66:67], v[120:121], v[120:121], v[66:67]
	v_mul_f32_e32 v64, v121, v121
	v_pk_add_f32 v[66:67], v[64:65], v[66:67] op_sel_hi:[0,1]
	v_pk_fma_f32 v[66:67], v[118:119], v[118:119], v[66:67]
	v_mul_f32_e32 v64, v119, v119
	v_pk_add_f32 v[66:67], v[64:65], v[66:67] op_sel_hi:[0,1]
	v_pk_fma_f32 v[66:67], v[92:93], v[92:93], v[66:67]
	v_mul_f32_e32 v64, v93, v93
	v_pk_add_f32 v[66:67], v[64:65], v[66:67] op_sel_hi:[0,1]
	v_pk_fma_f32 v[66:67], v[90:91], v[90:91], v[66:67]
	v_mul_f32_e32 v64, v91, v91
	v_pk_add_f32 v[66:67], v[64:65], v[66:67] op_sel_hi:[0,1]
	v_pk_fma_f32 v[66:67], v[114:115], v[114:115], v[66:67]
	v_mul_f32_e32 v64, v115, v115
	v_pk_add_f32 v[66:67], v[64:65], v[66:67] op_sel_hi:[0,1]
	v_pk_fma_f32 v[66:67], v[106:107], v[106:107], v[66:67]
	v_mul_f32_e32 v64, v107, v107
	v_pk_add_f32 v[66:67], v[64:65], v[66:67] op_sel_hi:[0,1]
	v_pk_fma_f32 v[66:67], v[98:99], v[98:99], v[66:67]
	v_mul_f32_e32 v64, v99, v99
	v_pk_add_f32 v[66:67], v[64:65], v[66:67] op_sel_hi:[0,1]
	v_pk_fma_f32 v[66:67], v[94:95], v[94:95], v[66:67]
	v_mul_f32_e32 v64, v95, v95
	v_pk_add_f32 v[66:67], v[64:65], v[66:67] op_sel_hi:[0,1]
	v_pk_fma_f32 v[66:67], v[116:117], v[116:117], v[66:67]
	v_mul_f32_e32 v64, v117, v117
	v_pk_add_f32 v[66:67], v[64:65], v[66:67] op_sel_hi:[0,1]
	v_pk_fma_f32 v[66:67], v[112:113], v[112:113], v[66:67]
	v_mul_f32_e32 v64, v113, v113
	v_pk_add_f32 v[66:67], v[64:65], v[66:67] op_sel_hi:[0,1]
	v_pk_fma_f32 v[66:67], v[100:101], v[100:101], v[66:67]
	v_mul_f32_e32 v64, v101, v101
	v_pk_add_f32 v[66:67], v[64:65], v[66:67] op_sel_hi:[0,1]
	v_pk_fma_f32 v[66:67], v[96:97], v[96:97], v[66:67]
	v_mul_f32_e32 v64, v97, v97
	v_pk_add_f32 v[134:135], v[64:65], v[66:67] op_sel_hi:[0,1]
	v_mov_b32_e32 v66, v65
	v_mov_b32_e32 v67, v65
	v_mov_b32_e32 v146, v134
	v_mov_b32_e32 v64, v65
	v_mov_b64_e32 v[68:69], v[66:67]
	v_permlane32_swap_b32_e32 v134, v146
	v_mov_b64_e32 v[66:67], v[64:65]
	s_and_saveexec_b64 s[4:5], s[6:7]
	s_cbranch_execz .LBB0_1080
	v_lshl_add_u64 v[66:67], s[14:15], 0, v[110:111]
